# S5-out scan loop head aligned to 64 B on top of GEMM K-loop loop-edge edits
# baseline (speedup 1.0000x reference)
; #define GAS __attribute__((address_space(1)))
; __device__ __forceinline__ void fx_add(long long* p, float v, float scale) { __hip_atomic_fetch_add((GAS long long*)p, (long long)__float2ll_rn(v * scale), __ATOMIC_RELAXED, __HIP_MEMORY_SCOPE_AGENT); }
; #define LDS_WAIT() asm volatile("s_waitcnt lgkmcnt(0)" ::: "memory")
; template <bool PB>
; __device__ __forceinline__ void phase_s5(const PView& p, int l, LAS unsigned char* lds, int lane, int wave) {
;     ...
;         for (int sc = 0; sc < SEGLEN / 16; ++sc) {
;             const int pos0 = t0 + 16 * sc;
;             const int scn = (sc + 2 < SEGLEN / 16) ? sc + 2 : SEGLEN / 16 - 1;
;             const bf16x8 ufC = *(const GAS bf16x8*)(up + (size_t)scn * 16 * DIN);
;     ...
;                 ss += __shfl_xor(ss, 16); ss += __shfl_xor(ss, 32);
;                 if (q == 0) fx_add(rs2 + pos0 + c, ss, FX_RS);
;                 LDS_WAIT();
;             }
;             ufA = ufB; ufB = ufC;
.LBB0_333:
	s_or_b64 exec, exec, s[10:11]
	s_waitcnt lgkmcnt(0)
	v_mov_b64_e32 v[168:169], v[80:81]
	v_mov_b64_e32 v[170:171], v[82:83]
	v_mov_b64_e32 v[82:83], v[70:71]
	s_add_i32 s26, s26, 1
	v_mov_b64_e32 v[80:81], v[68:69]
	s_waitcnt vmcnt(2)
	v_mov_b64_e32 v[68:69], v[76:77]
	v_lshl_add_u64 v[114:115], v[114:115], 0, s[90:91]
	v_add_u32_e32 v116, 16, v116
	v_swap_b32 v160, v161
	v_swap_b32 v162, v163
	s_cmp_eq_u32 s26, 33
	v_mov_b64_e32 v[70:71], v[78:79]
	s_cbranch_scc1 .LBB0_253
	.p2align 6
